# v51 + kpair MFMA order in the out-projection loop too (all four GEMM loops)
# speedup vs baseline: 1.0127x; 1.0057x over previous
; #define PG8_STAGE(bufoff, gbase, voff) do { _Pragma("unroll") for (int _i = 0; _i < 2; ++_i) \
;         __builtin_amdgcn_global_load_lds((const unsigned*)((const char*)(gbase) + (voff)[_i]), (PG8_LAS unsigned*)(lds + (bufoff) + ldsw + _i * 8192), 16, 0, 0); } while (0)
; #define PG8_LDA(dst, b, h) do { _Pragma("unroll") for (int m = 0; m < 4; ++m) _Pragma("unroll") for (int k = 0; k < 2; ++k) dst[m][k] = *(const PG8_LAS bf16x8*)(lds + PG8_SA(b, h) + aoff + m * 2048 + k * 1024); } while (0)
; #define PG8_LDB(dst, b, h) do { _Pragma("unroll") for (int n = 0; n < 2; ++n) _Pragma("unroll") for (int k = 0; k < 2; ++k) dst[n][k] = *(const PG8_LAS bf16x8*)(lds + PG8_SB(b, h) + boff + n * 2048 + k * 1024); } while (0)
; #define PG8_MMA(ai, bj, At, Bt) do { __builtin_amdgcn_s_setprio(1); _Pragma("unroll") for (int m = 0; m < 4; ++m) _Pragma("unroll") for (int n = 0; n < 2; ++n) _Pragma("unroll") for (int k = 0; k < 2; ++k) \
;         acc[ai][bj][m][n] = __builtin_amdgcn_mfma_f32_16x16x32_bf16(Bt[n][k], At[m][k], acc[ai][bj][m][n], 0, 0, 0); __builtin_amdgcn_s_setprio(0); } while (0)
; #define PG8_WAIT_L(n) asm volatile("s_waitcnt lgkmcnt(" #n ")" ::: "memory")
; #define PG8_BAR __builtin_amdgcn_s_barrier()
; #define PG8_SCHED __builtin_amdgcn_sched_barrier(0)
; template <class Epi, class Sched, bool ALIGN_EPI = false, bool SP2 = false>
; __device__ __forceinline__ void gemm_phase(PG8_LAS unsigned char* lds, const Gemm g, const Sched& S, const Epi& E) {
;     ...
;             PG8_LDB(B0, 0, 0); PG8_SCHED; PG8_LDA(At, 0, 0); PG8_STAGE(PG8_SA(1, 1), a1 + hstep, voffA);
;             PG8_WAIT_L(8); PG8_BAR; PG8_WAIT_L(0); PG8_MMA(0, 0, At, B0); PG8_BAR; PG8_SCHED;
;             PG8_LDB(B1, 0, 1); PG8_STAGE(PG8_SB(0, 0), b2, voffB);
;             PG8_BAR; PG8_WAIT_L(0); PG8_MMA(0, 1, At, B1); PG8_BAR;
;             PG8_LDA(At, 0, 1); PG8_STAGE(PG8_SA(0, 0), a2, voffA);
;             PG8_BAR; PG8_WAIT_L(0); PG8_MMA(1, 0, At, B0); PG8_BAR; PG8_SCHED;
.LBB0_911:
	v_add_u32_e32 v3, s83, v219
	ds_read_b128 v[98:101], v3
	ds_read_b128 v[102:105], v3 offset:1024
	ds_read_b128 v[106:109], v3 offset:2048
	ds_read_b128 v[166:169], v3 offset:3072
	v_add_u32_e32 v3, s86, v219
	s_add_u32 s62, s58, s60
	ds_read_b128 v[170:173], v3
	ds_read_b128 v[174:177], v3 offset:1024
	ds_read_b128 v[178:181], v3 offset:2048
	ds_read_b128 v[182:185], v3 offset:3072
	s_addc_u32 s63, s59, s61
	s_add_u32 s62, s62, 0x100
	s_addc_u32 s63, s63, 0
	s_add_u32 s93, s90, s60
	s_addc_u32 s94, s91, s61
	s_cmpk_eq_i32 s60, 0x1f00
	s_cselect_b32 s65, s19, s63
	s_cselect_b32 s64, s21, s62
	s_cselect_b32 s63, s53, s94
	s_cselect_b32 s62, s57, s93
	v_lshl_add_u64 v[4:5], v[94:95], 0, s[60:61]
	s_add_i32 m0, s24, 0xc000
	ds_read_b128 v[186:189], v244
	ds_read_b128 v[190:193], v244 offset:1024
	ds_read_b128 v[196:199], v244 offset:2048
	ds_read_b128 v[200:203], v244 offset:3072
	ds_read_b128 v[204:207], v244 offset:4096
	ds_read_b128 v[208:211], v244 offset:5120
	ds_read_b128 v[212:215], v244 offset:6144
	ds_read_b128 v[246:249], v244 offset:7168
	global_load_lds_dwordx4 v[4:5], off
	v_lshl_add_u64 v[4:5], v[96:97], 0, s[60:61]
	s_add_i32 m0, s24, 0xe000
	s_nop 0
	global_load_lds_dwordx4 v[4:5], off
	s_waitcnt vmcnt(8)
	s_waitcnt lgkmcnt(0)
	s_barrier
	s_setprio 1
	s_waitcnt lgkmcnt(0)
	v_mfma_f32_16x16x32_bf16 v[146:149], v[98:101], v[186:189], v[146:149]
	v_mfma_f32_16x16x32_bf16 v[146:149], v[102:105], v[190:193], v[146:149]
	v_mfma_f32_16x16x32_bf16 v[142:145], v[106:109], v[186:189], v[142:145]
	v_mfma_f32_16x16x32_bf16 v[142:145], v[166:169], v[190:193], v[142:145]
	v_mfma_f32_16x16x32_bf16 v[138:141], v[98:101], v[196:199], v[138:141]
	v_mfma_f32_16x16x32_bf16 v[138:141], v[102:105], v[200:203], v[138:141]
	v_mfma_f32_16x16x32_bf16 v[134:137], v[106:109], v[196:199], v[134:137]
	v_mfma_f32_16x16x32_bf16 v[134:137], v[166:169], v[200:203], v[134:137]
	v_mfma_f32_16x16x32_bf16 v[130:133], v[98:101], v[204:207], v[130:133]
	v_mfma_f32_16x16x32_bf16 v[130:133], v[102:105], v[208:211], v[130:133]
	v_mfma_f32_16x16x32_bf16 v[126:129], v[106:109], v[204:207], v[126:129]
	v_mfma_f32_16x16x32_bf16 v[126:129], v[166:169], v[208:211], v[126:129]
	v_mfma_f32_16x16x32_bf16 v[122:125], v[98:101], v[212:215], v[122:125]
	v_mfma_f32_16x16x32_bf16 v[122:125], v[102:105], v[246:249], v[122:125]
	v_mfma_f32_16x16x32_bf16 v[118:121], v[106:109], v[212:215], v[118:121]
	v_mfma_f32_16x16x32_bf16 v[118:121], v[166:169], v[246:249], v[118:121]
	s_setprio 0
	s_setprio 1
	v_mfma_f32_16x16x32_bf16 v[66:69], v[170:173], v[186:189], v[66:69]
	v_mfma_f32_16x16x32_bf16 v[66:69], v[174:177], v[190:193], v[66:69]
	v_mfma_f32_16x16x32_bf16 v[62:65], v[178:181], v[186:189], v[62:65]
	v_mfma_f32_16x16x32_bf16 v[62:65], v[182:185], v[190:193], v[62:65]
	v_mfma_f32_16x16x32_bf16 v[58:61], v[170:173], v[196:199], v[58:61]
	v_mfma_f32_16x16x32_bf16 v[58:61], v[174:177], v[200:203], v[58:61]
	v_mfma_f32_16x16x32_bf16 v[54:57], v[178:181], v[196:199], v[54:57]
	v_mfma_f32_16x16x32_bf16 v[54:57], v[182:185], v[200:203], v[54:57]
	v_mfma_f32_16x16x32_bf16 v[50:53], v[170:173], v[204:207], v[50:53]
	v_mfma_f32_16x16x32_bf16 v[50:53], v[174:177], v[208:211], v[50:53]
	v_mfma_f32_16x16x32_bf16 v[46:49], v[178:181], v[204:207], v[46:49]
	v_mfma_f32_16x16x32_bf16 v[46:49], v[182:185], v[208:211], v[46:49]
	v_mfma_f32_16x16x32_bf16 v[42:45], v[170:173], v[212:215], v[42:45]
	v_mfma_f32_16x16x32_bf16 v[42:45], v[174:177], v[246:249], v[42:45]
	v_mfma_f32_16x16x32_bf16 v[38:41], v[178:181], v[212:215], v[38:41]
	v_mfma_f32_16x16x32_bf16 v[38:41], v[182:185], v[246:249], v[38:41]
	s_setprio 0
	s_barrier
	s_add_i32 s93, s83, s2
	v_lshl_add_u64 v[216:217], s[62:63], 0, v[152:153]
	s_mov_b32 m0, s93
	ds_read_b128 v[186:189], v244 offset:16384
	ds_read_b128 v[190:193], v244 offset:17408
	ds_read_b128 v[196:199], v244 offset:18432
	ds_read_b128 v[200:203], v244 offset:19456
	ds_read_b128 v[204:207], v244 offset:20480
	ds_read_b128 v[208:211], v244 offset:21504
	ds_read_b128 v[212:215], v244 offset:22528
	ds_read_b128 v[246:249], v244 offset:23552
	global_load_lds_dwordx4 v[216:217], off
	s_add_i32 m0, s93, 0x2000
	s_add_u32 s94, s62, 0x100000
	v_lshl_add_u64 v[250:251], s[62:63], 0, v[156:157]
	s_addc_u32 s95, s63, 0
	s_add_i32 s93, s86, s2
	global_load_lds_dwordx4 v[250:251], off
	v_lshl_add_u64 v[4:5], s[94:95], 0, v[152:153]
	s_mov_b32 m0, s93
	v_lshl_add_u64 v[252:253], s[64:65], 0, v[150:151]
	global_load_lds_dwordx4 v[4:5], off
	v_lshl_add_u64 v[4:5], s[94:95], 0, v[156:157]
	s_add_i32 m0, s93, 0x2000
	v_lshl_add_u64 v[222:223], s[64:65], 0, v[154:155]
	global_load_lds_dwordx4 v[4:5], off
	s_mov_b32 m0, s24
	s_nop 0
	global_load_lds_dwordx4 v[252:253], off
	s_mov_b32 m0, s25
	s_nop 0
	global_load_lds_dwordx4 v[222:223], off
	s_waitcnt vmcnt(8)
	s_waitcnt lgkmcnt(0)
	s_barrier
; #define PG8_STAGE(bufoff, gbase, voff) do { _Pragma("unroll") for (int _i = 0; _i < 2; ++_i) \
;         __builtin_amdgcn_global_load_lds((const unsigned*)((const char*)(gbase) + (voff)[_i]), (PG8_LAS unsigned*)(lds + (bufoff) + ldsw + _i * 8192), 16, 0, 0); } while (0)
; #define PG8_LDA(dst, b, h) do { _Pragma("unroll") for (int m = 0; m < 4; ++m) _Pragma("unroll") for (int k = 0; k < 2; ++k) dst[m][k] = *(const PG8_LAS bf16x8*)(lds + PG8_SA(b, h) + aoff + m * 2048 + k * 1024); } while (0)
; #define PG8_LDB(dst, b, h) do { _Pragma("unroll") for (int n = 0; n < 2; ++n) _Pragma("unroll") for (int k = 0; k < 2; ++k) dst[n][k] = *(const PG8_LAS bf16x8*)(lds + PG8_SB(b, h) + boff + n * 2048 + k * 1024); } while (0)
; #define PG8_MMA(ai, bj, At, Bt) do { __builtin_amdgcn_s_setprio(1); _Pragma("unroll") for (int m = 0; m < 4; ++m) _Pragma("unroll") for (int n = 0; n < 2; ++n) _Pragma("unroll") for (int k = 0; k < 2; ++k) \
;         acc[ai][bj][m][n] = __builtin_amdgcn_mfma_f32_16x16x32_bf16(Bt[n][k], At[m][k], acc[ai][bj][m][n], 0, 0, 0); __builtin_amdgcn_s_setprio(0); } while (0)
; #define PG8_WAIT_V(n) asm volatile("s_waitcnt vmcnt(" #n ")" ::: "memory")
; #define PG8_WAIT_L(n) asm volatile("s_waitcnt lgkmcnt(" #n ")" ::: "memory")
; #define PG8_BAR __builtin_amdgcn_s_barrier()
; #define PG8_SCHED __builtin_amdgcn_sched_barrier(0)
; template <class Epi, class Sched, bool ALIGN_EPI = false, bool SP2 = false>
; __device__ __forceinline__ void gemm_phase(PG8_LAS unsigned char* lds, const Gemm g, const Sched& S, const Epi& E) {
;     ...
;             PG8_BAR; PG8_WAIT_L(0); PG8_MMA(1, 0, At, B0); PG8_BAR; PG8_SCHED;
;             PG8_STAGE(PG8_SB(0, 1), b2 + hstep, voffB);
;             PG8_WAIT_V(6); PG8_BAR; PG8_MMA(1, 1, At, B1); PG8_BAR;
;             PG8_LDB(B0, 1, 0); PG8_SCHED; PG8_LDA(At, 1, 0); PG8_STAGE(PG8_SA(0, 1), a2 + hstep, voffA);
;             PG8_WAIT_L(8); PG8_BAR; PG8_WAIT_L(0); PG8_MMA(0, 0, At, B0); PG8_BAR; PG8_SCHED;
	s_setprio 1
	s_waitcnt lgkmcnt(0)
	v_mfma_f32_16x16x32_bf16 v[114:117], v[98:101], v[186:189], v[114:117]
	v_mfma_f32_16x16x32_bf16 v[114:117], v[102:105], v[190:193], v[114:117]
	v_mfma_f32_16x16x32_bf16 v[110:113], v[106:109], v[186:189], v[110:113]
	v_mfma_f32_16x16x32_bf16 v[110:113], v[166:169], v[190:193], v[110:113]
	v_mfma_f32_16x16x32_bf16 v[90:93], v[98:101], v[196:199], v[90:93]
	v_mfma_f32_16x16x32_bf16 v[90:93], v[102:105], v[200:203], v[90:93]
	v_mfma_f32_16x16x32_bf16 v[86:89], v[106:109], v[196:199], v[86:89]
	v_mfma_f32_16x16x32_bf16 v[86:89], v[166:169], v[200:203], v[86:89]
	v_mfma_f32_16x16x32_bf16 v[82:85], v[98:101], v[204:207], v[82:85]
	v_mfma_f32_16x16x32_bf16 v[82:85], v[102:105], v[208:211], v[82:85]
	v_mfma_f32_16x16x32_bf16 v[78:81], v[106:109], v[204:207], v[78:81]
	v_mfma_f32_16x16x32_bf16 v[78:81], v[166:169], v[208:211], v[78:81]
	v_mfma_f32_16x16x32_bf16 v[74:77], v[98:101], v[212:215], v[74:77]
	v_mfma_f32_16x16x32_bf16 v[74:77], v[102:105], v[246:249], v[74:77]
	v_mfma_f32_16x16x32_bf16 v[70:73], v[106:109], v[212:215], v[70:73]
	v_mfma_f32_16x16x32_bf16 v[70:73], v[166:169], v[246:249], v[70:73]
	s_setprio 0
	s_setprio 1
	v_mfma_f32_16x16x32_bf16 v[34:37], v[170:173], v[186:189], v[34:37]
	v_mfma_f32_16x16x32_bf16 v[34:37], v[174:177], v[190:193], v[34:37]
	v_mfma_f32_16x16x32_bf16 v[30:33], v[178:181], v[186:189], v[30:33]
	v_mfma_f32_16x16x32_bf16 v[30:33], v[182:185], v[190:193], v[30:33]
	v_mfma_f32_16x16x32_bf16 v[26:29], v[170:173], v[196:199], v[26:29]
	v_mfma_f32_16x16x32_bf16 v[26:29], v[174:177], v[200:203], v[26:29]
	v_mfma_f32_16x16x32_bf16 v[22:25], v[178:181], v[196:199], v[22:25]
	v_mfma_f32_16x16x32_bf16 v[22:25], v[182:185], v[200:203], v[22:25]
	v_mfma_f32_16x16x32_bf16 v[18:21], v[170:173], v[204:207], v[18:21]
	v_mfma_f32_16x16x32_bf16 v[18:21], v[174:177], v[208:211], v[18:21]
	v_mfma_f32_16x16x32_bf16 v[14:17], v[178:181], v[204:207], v[14:17]
	v_mfma_f32_16x16x32_bf16 v[14:17], v[182:185], v[208:211], v[14:17]
	v_mfma_f32_16x16x32_bf16 v[10:13], v[170:173], v[212:215], v[10:13]
	v_mfma_f32_16x16x32_bf16 v[10:13], v[174:177], v[246:249], v[10:13]
	v_mfma_f32_16x16x32_bf16 v[4:7], v[178:181], v[212:215], v[6:9]
	v_mfma_f32_16x16x32_bf16 v[4:7], v[182:185], v[246:249], v[4:7]
	s_setprio 0
	s_barrier
	s_add_i32 s93, 0, 0x18000
	v_add_u32_e32 v3, s93, v219
	s_add_i32 s94, 0, 0x1c000
	ds_read_b128 v[98:101], v3
	ds_read_b128 v[102:105], v3 offset:1024
	ds_read_b128 v[106:109], v3 offset:2048
	ds_read_b128 v[166:169], v3 offset:3072
	v_add_u32_e32 v3, s94, v219
	ds_read_b128 v[170:173], v3
	ds_read_b128 v[174:177], v3 offset:1024
	ds_read_b128 v[178:181], v3 offset:2048
	ds_read_b128 v[182:185], v3 offset:3072
	s_add_u32 s64, s64, 0x100000
	s_addc_u32 s65, s65, 0
	s_mov_b32 m0, s26
	v_lshl_add_u64 v[8:9], s[64:65], 0, v[150:151]
	ds_read_b128 v[186:189], v244 offset:32768
	ds_read_b128 v[190:193], v244 offset:33792
	ds_read_b128 v[196:199], v244 offset:34816
	ds_read_b128 v[200:203], v244 offset:35840
	ds_read_b128 v[204:207], v244 offset:36864
	ds_read_b128 v[208:211], v244 offset:37888
	ds_read_b128 v[212:215], v244 offset:38912
	ds_read_b128 v[246:249], v244 offset:39936
	global_load_lds_dwordx4 v[8:9], off
	v_lshl_add_u64 v[8:9], s[64:65], 0, v[154:155]
	s_mov_b32 m0, s27
	s_nop 0
	global_load_lds_dwordx4 v[8:9], off
	s_waitcnt vmcnt(8)
	s_waitcnt lgkmcnt(0)
	s_barrier
	s_setprio 1
	s_waitcnt lgkmcnt(0)
	v_mfma_f32_16x16x32_bf16 v[146:149], v[98:101], v[186:189], v[146:149]
	v_mfma_f32_16x16x32_bf16 v[146:149], v[102:105], v[190:193], v[146:149]
	v_mfma_f32_16x16x32_bf16 v[142:145], v[106:109], v[186:189], v[142:145]
	v_mfma_f32_16x16x32_bf16 v[142:145], v[166:169], v[190:193], v[142:145]
	v_mfma_f32_16x16x32_bf16 v[138:141], v[98:101], v[196:199], v[138:141]
	v_mfma_f32_16x16x32_bf16 v[138:141], v[102:105], v[200:203], v[138:141]
	v_mfma_f32_16x16x32_bf16 v[134:137], v[106:109], v[196:199], v[134:137]
	v_mfma_f32_16x16x32_bf16 v[134:137], v[166:169], v[200:203], v[134:137]
	v_mfma_f32_16x16x32_bf16 v[130:133], v[98:101], v[204:207], v[130:133]
	v_mfma_f32_16x16x32_bf16 v[130:133], v[102:105], v[208:211], v[130:133]
	v_mfma_f32_16x16x32_bf16 v[126:129], v[106:109], v[204:207], v[126:129]
	v_mfma_f32_16x16x32_bf16 v[126:129], v[166:169], v[208:211], v[126:129]
	v_mfma_f32_16x16x32_bf16 v[122:125], v[98:101], v[212:215], v[122:125]
	v_mfma_f32_16x16x32_bf16 v[122:125], v[102:105], v[246:249], v[122:125]
	v_mfma_f32_16x16x32_bf16 v[118:121], v[106:109], v[212:215], v[118:121]
	v_mfma_f32_16x16x32_bf16 v[118:121], v[166:169], v[246:249], v[118:121]
	s_setprio 0
	s_setprio 1
	v_mfma_f32_16x16x32_bf16 v[66:69], v[170:173], v[186:189], v[66:69]
	v_mfma_f32_16x16x32_bf16 v[66:69], v[174:177], v[190:193], v[66:69]
	v_mfma_f32_16x16x32_bf16 v[62:65], v[178:181], v[186:189], v[62:65]
	v_mfma_f32_16x16x32_bf16 v[62:65], v[182:185], v[190:193], v[62:65]
	v_mfma_f32_16x16x32_bf16 v[58:61], v[170:173], v[196:199], v[58:61]
	v_mfma_f32_16x16x32_bf16 v[58:61], v[174:177], v[200:203], v[58:61]
	v_mfma_f32_16x16x32_bf16 v[54:57], v[178:181], v[196:199], v[54:57]
	v_mfma_f32_16x16x32_bf16 v[54:57], v[182:185], v[200:203], v[54:57]
	v_mfma_f32_16x16x32_bf16 v[50:53], v[170:173], v[204:207], v[50:53]
	v_mfma_f32_16x16x32_bf16 v[50:53], v[174:177], v[208:211], v[50:53]
	v_mfma_f32_16x16x32_bf16 v[46:49], v[178:181], v[204:207], v[46:49]
	v_mfma_f32_16x16x32_bf16 v[46:49], v[182:185], v[208:211], v[46:49]
	v_mfma_f32_16x16x32_bf16 v[42:45], v[170:173], v[212:215], v[42:45]
	v_mfma_f32_16x16x32_bf16 v[42:45], v[174:177], v[246:249], v[42:45]
	v_mfma_f32_16x16x32_bf16 v[38:41], v[178:181], v[212:215], v[38:41]
	v_mfma_f32_16x16x32_bf16 v[38:41], v[182:185], v[246:249], v[38:41]
	s_setprio 0
	s_barrier
; #define PG8_STAGE(bufoff, gbase, voff) do { _Pragma("unroll") for (int _i = 0; _i < 2; ++_i) \
;         __builtin_amdgcn_global_load_lds((const unsigned*)((const char*)(gbase) + (voff)[_i]), (PG8_LAS unsigned*)(lds + (bufoff) + ldsw + _i * 8192), 16, 0, 0); } while (0)
; #define PG8_LDA(dst, b, h) do { _Pragma("unroll") for (int m = 0; m < 4; ++m) _Pragma("unroll") for (int k = 0; k < 2; ++k) dst[m][k] = *(const PG8_LAS bf16x8*)(lds + PG8_SA(b, h) + aoff + m * 2048 + k * 1024); } while (0)
; #define PG8_MMA(ai, bj, At, Bt) do { __builtin_amdgcn_s_setprio(1); _Pragma("unroll") for (int m = 0; m < 4; ++m) _Pragma("unroll") for (int n = 0; n < 2; ++n) _Pragma("unroll") for (int k = 0; k < 2; ++k) \
;         acc[ai][bj][m][n] = __builtin_amdgcn_mfma_f32_16x16x32_bf16(Bt[n][k], At[m][k], acc[ai][bj][m][n], 0, 0, 0); __builtin_amdgcn_s_setprio(0); } while (0)
; #define PG8_WAIT_V(n) asm volatile("s_waitcnt vmcnt(" #n ")" ::: "memory")
; #define PG8_WAIT_L(n) asm volatile("s_waitcnt lgkmcnt(" #n ")" ::: "memory")
; #define PG8_BAR __builtin_amdgcn_s_barrier()
; #define PG8_SCHED __builtin_amdgcn_sched_barrier(0)
; template <class Epi, class Sched, bool ALIGN_EPI = false, bool SP2 = false>
; __device__ __forceinline__ void gemm_phase(PG8_LAS unsigned char* lds, const Gemm g, const Sched& S, const Epi& E) {
;     ...
;             PG8_LDA(At, 1, 1); PG8_STAGE(PG8_SA(1, 0), a3, voffA);
;             PG8_BAR; PG8_WAIT_L(0); PG8_MMA(1, 0, At, B0); PG8_BAR; PG8_SCHED;
;             PG8_STAGE(PG8_SB(1, 1), b3 + hstep, voffB);
;             PG8_WAIT_V(6); PG8_BAR; PG8_MMA(1, 1, At, B1); PG8_BAR;
	s_add_i32 s64, s93, s2
	v_lshl_add_u64 v[8:9], v[216:217], 0, s[14:15]
	s_mov_b32 m0, s64
	ds_read_b128 v[186:189], v244 offset:49152
	ds_read_b128 v[190:193], v244 offset:50176
	ds_read_b128 v[196:199], v244 offset:51200
	ds_read_b128 v[200:203], v244 offset:52224
	ds_read_b128 v[204:207], v244 offset:53248
	ds_read_b128 v[208:211], v244 offset:54272
	ds_read_b128 v[212:215], v244 offset:55296
	ds_read_b128 v[246:249], v244 offset:56320
	global_load_lds_dwordx4 v[8:9], off
	s_add_i32 m0, s64, 0x2000
	s_add_u32 s62, s62, 0x100080
	v_lshl_add_u64 v[8:9], v[250:251], 0, s[14:15]
	s_addc_u32 s63, s63, 0
	s_add_i32 s64, s94, s2
	global_load_lds_dwordx4 v[8:9], off
	v_lshl_add_u64 v[8:9], s[62:63], 0, v[152:153]
	s_mov_b32 m0, s64
	s_nop 0
	global_load_lds_dwordx4 v[8:9], off
	v_lshl_add_u64 v[8:9], s[62:63], 0, v[156:157]
	s_add_i32 m0, s64, 0x2000
	s_nop 0
	global_load_lds_dwordx4 v[8:9], off
	v_lshl_add_u64 v[8:9], v[252:253], 0, s[14:15]
	s_mov_b32 m0, s66
	s_nop 0
	global_load_lds_dwordx4 v[8:9], off
	v_lshl_add_u64 v[8:9], v[222:223], 0, s[14:15]
	s_mov_b32 m0, s67
	s_nop 0
	global_load_lds_dwordx4 v[8:9], off
	s_waitcnt vmcnt(8)
	s_waitcnt lgkmcnt(0)
	s_barrier
	s_setprio 1
	s_waitcnt lgkmcnt(0)
	v_mfma_f32_16x16x32_bf16 v[114:117], v[98:101], v[186:189], v[114:117]
	v_mfma_f32_16x16x32_bf16 v[114:117], v[102:105], v[190:193], v[114:117]
	v_mfma_f32_16x16x32_bf16 v[110:113], v[106:109], v[186:189], v[110:113]
	v_mfma_f32_16x16x32_bf16 v[110:113], v[166:169], v[190:193], v[110:113]
	v_mfma_f32_16x16x32_bf16 v[90:93], v[98:101], v[196:199], v[90:93]
	v_mfma_f32_16x16x32_bf16 v[90:93], v[102:105], v[200:203], v[90:93]
	v_mfma_f32_16x16x32_bf16 v[86:89], v[106:109], v[196:199], v[86:89]
	v_mfma_f32_16x16x32_bf16 v[86:89], v[166:169], v[200:203], v[86:89]
	v_mfma_f32_16x16x32_bf16 v[82:85], v[98:101], v[204:207], v[82:85]
	v_mfma_f32_16x16x32_bf16 v[82:85], v[102:105], v[208:211], v[82:85]
	v_mfma_f32_16x16x32_bf16 v[78:81], v[106:109], v[204:207], v[78:81]
	v_mfma_f32_16x16x32_bf16 v[78:81], v[166:169], v[208:211], v[78:81]
	v_mfma_f32_16x16x32_bf16 v[74:77], v[98:101], v[212:215], v[74:77]
	v_mfma_f32_16x16x32_bf16 v[74:77], v[102:105], v[246:249], v[74:77]
	v_mfma_f32_16x16x32_bf16 v[70:73], v[106:109], v[212:215], v[70:73]
	v_mfma_f32_16x16x32_bf16 v[70:73], v[166:169], v[246:249], v[70:73]
	s_setprio 0
	s_setprio 1
	v_mfma_f32_16x16x32_bf16 v[34:37], v[170:173], v[186:189], v[34:37]
	v_mfma_f32_16x16x32_bf16 v[34:37], v[174:177], v[190:193], v[34:37]
	v_mfma_f32_16x16x32_bf16 v[30:33], v[178:181], v[186:189], v[30:33]
	v_mfma_f32_16x16x32_bf16 v[30:33], v[182:185], v[190:193], v[30:33]
	v_mfma_f32_16x16x32_bf16 v[26:29], v[170:173], v[196:199], v[26:29]
	v_mfma_f32_16x16x32_bf16 v[26:29], v[174:177], v[200:203], v[26:29]
	v_mfma_f32_16x16x32_bf16 v[22:25], v[178:181], v[196:199], v[22:25]
	v_mfma_f32_16x16x32_bf16 v[22:25], v[182:185], v[200:203], v[22:25]
	v_mfma_f32_16x16x32_bf16 v[18:21], v[170:173], v[204:207], v[18:21]
	v_mfma_f32_16x16x32_bf16 v[18:21], v[174:177], v[208:211], v[18:21]
	v_mfma_f32_16x16x32_bf16 v[14:17], v[178:181], v[204:207], v[14:17]
	v_mfma_f32_16x16x32_bf16 v[14:17], v[182:185], v[208:211], v[14:17]
	v_mfma_f32_16x16x32_bf16 v[8:11], v[170:173], v[212:215], v[10:13]
	v_mfma_f32_16x16x32_bf16 v[10:13], v[174:177], v[246:249], v[8:11]
	v_mfma_f32_16x16x32_bf16 v[4:7], v[178:181], v[212:215], v[4:7]
	v_mfma_f32_16x16x32_bf16 v[6:9], v[182:185], v[246:249], v[4:7]
	s_setprio 0
	s_barrier
	s_add_i32 s92, s92, 2
	s_add_u32 s60, s60, 0x100
	s_addc_u32 s61, s61, 0
	s_cmp_gt_u32 s92, 61
	s_cbranch_scc1 .LBB0_914
